# diff-mixer stop vote: first ALiBi bias value recomputed in registers instead of an LDS read + full wait at the end of each voting step; stacked on the all-edits version
# speedup vs baseline: 1.0122x; 1.0122x over previous
.LBB0_264:
	s_add_i32 s100, s29, 64
	v_cvt_f32_i32_e32 v190, s100
	v_mul_f32_e32 v190, v208, v190
	v_pk_add_f32 v[66:67], v[198:199], v[190:191]
	s_nop 0
	v_cmp_gt_f32_e32 vcc, v66, v67
	s_cmp_lg_u64 vcc, 0
	s_cselect_b64 s[10:11], -1, 0
	s_and_saveexec_b64 s[12:13], s[42:43]
	v_cndmask_b32_e64 v0, 0, 1, s[10:11]
	v_mov_b32_e32 v66, s24
	ds_write_b32 v66, v0
	s_or_b64 exec, exec, s[12:13]
	s_xor_b64 s[10:11], s[10:11], -1
	s_or_b64 s[6:7], s[10:11], s[6:7]

.LBB0_291:
	v_cvt_f32_i32_e32 v188, s29
	v_mul_f32_e32 v188, v208, v188
	v_pk_add_f32 v[66:67], v[198:199], v[188:189]
	s_nop 0
	v_cmp_gt_f32_e32 vcc, v66, v67
	s_cmp_lg_u64 vcc, 0
	s_cselect_b64 s[10:11], -1, 0
	s_and_saveexec_b64 s[12:13], s[42:43]
	v_cndmask_b32_e64 v0, 0, 1, s[10:11]
	v_mov_b32_e32 v66, s24
	ds_write_b32 v66, v0 offset:32
	s_or_b64 exec, exec, s[12:13]
	s_xor_b64 s[10:11], s[10:11], -1
	s_or_b64 s[6:7], s[10:11], s[6:7]
